# younger-workgroup K-loop priority raise at level 3 instead of 1
# speedup vs baseline: 1.0038x; 1.0021x over previous
.LBB0_60:
	s_mov_b64 s[6:7], -1
	s_and_b64 vcc, exec, s[4:5]
	s_cbranch_vccz .LBB0_52
	v_mov_b32_e32 v71, v139
	v_readlane_b32 s52, v246, 25
	v_ashrrev_i32_e32 v68, 6, v71
	s_waitcnt vmcnt(48)
	v_lshlrev_b32_e32 v6, 3, v68
	v_bfe_u32 v70, v71, 3, 3
	v_or_b32_e32 v2, v6, v70
	v_lshrrev_b32_e32 v7, 1, v2
	s_lshl_b32 s5, s9, 7
	v_xor_b32_e32 v3, v7, v71
	v_readlane_b32 s54, v246, 27
	v_readlane_b32 s55, v246, 28
	v_readlane_b32 s36, v246, 9
	s_lshl_b32 s4, s10, 7
	v_add_u32_e32 v4, s5, v2
	v_mov_b64_e32 v[0:1], s[54:55]
	s_movk_i32 s9, 0x2080
	v_lshlrev_b32_e32 v3, 4, v3
	v_readlane_b32 s38, v246, 11
	v_readlane_b32 s39, v246, 12
	v_mad_i64_i32 v[0:1], s[6:7], v4, s9, v[0:1]
	v_and_b32_e32 v136, 0x70, v3
	v_add_u32_e32 v4, s4, v2
	v_mov_b64_e32 v[2:3], s[38:39]
	v_mad_i64_i32 v[2:3], s[6:7], v4, s9, v[2:3]
	v_lshlrev_b32_e32 v72, 10, v68
	v_add_u32_e32 v4, 0x4000, v72
	v_readfirstlane_b32 s6, v72
	v_lshl_add_u64 v[0:1], v[0:1], 0, v[136:137]
	s_mov_b32 m0, s6
	v_readfirstlane_b32 s6, v4
	v_add_u32_e32 v9, 0x1000, v72
	v_lshl_add_u64 v[2:3], v[2:3], 0, v[136:137]
	global_load_lds_dwordx4 v[0:1], off
	s_mov_b32 m0, s6
	s_mov_b64 s[10:11], 0x41000
	v_readfirstlane_b32 s6, v9
	v_add_u32_e32 v9, 0x5000, v72
	global_load_lds_dwordx4 v[2:3], off
	v_lshl_add_u64 v[4:5], v[0:1], 0, s[10:11]
	s_mov_b32 m0, s6
	v_readfirstlane_b32 s6, v9
	v_add_u32_e32 v9, 0x2000, v72
	global_load_lds_dwordx4 v[4:5], off
	v_lshl_add_u64 v[4:5], v[2:3], 0, s[10:11]
	s_mov_b32 m0, s6
	s_mov_b64 s[10:11], 0x82000
	v_readfirstlane_b32 s6, v9
	v_add_u32_e32 v9, 0x6000, v72
	global_load_lds_dwordx4 v[4:5], off
	v_lshl_add_u64 v[4:5], v[0:1], 0, s[10:11]
	s_mov_b32 m0, s6
	v_readfirstlane_b32 s6, v9
	global_load_lds_dwordx4 v[4:5], off
	v_lshl_add_u64 v[4:5], v[2:3], 0, s[10:11]
	s_mov_b32 m0, s6
	s_mov_b64 s[10:11], 0xc3000
	global_load_lds_dwordx4 v[4:5], off
	v_add_u32_e32 v4, 0x3000, v72
	v_lshl_add_u64 v[0:1], v[0:1], 0, s[10:11]
	v_readfirstlane_b32 s6, v4
	s_mov_b32 m0, s6
	v_bfe_u32 v75, v71, 4, 2
	global_load_lds_dwordx4 v[0:1], off
	v_lshl_add_u64 v[0:1], v[2:3], 0, s[10:11]
	v_add_u32_e32 v2, 0x7000, v72
	v_and_b32_e32 v76, 15, v71
	v_readfirstlane_b32 s6, v2
	s_mov_b32 m0, s6
	v_lshrrev_b32_e32 v8, 1, v71
	global_load_lds_dwordx4 v[0:1], off
	v_ashrrev_i32_e32 v1, 1, v71
	v_bfe_u32 v0, v71, 1, 3
	v_and_b32_e32 v69, 0xffffffc0, v1
	v_or_b32_e32 v1, v69, v76
	v_bitop3_b32 v0, v75, v0, 4 bitop3:0x36
	v_lshlrev_b32_e32 v73, 7, v1
	v_bitop3_b32 v1, v75, v8, 7 bitop3:0x78
	v_lshlrev_b32_e32 v77, 4, v0
	v_or_b32_e32 v0, s5, v70
	v_lshlrev_b32_e32 v78, 4, v1
	v_lshlrev_b32_e32 v1, 7, v71
	v_add_u32_e32 v0, v0, v6
	v_bitop3_b32 v2, v7, 7, v71 bitop3:0x48
	v_and_b32_e32 v74, 0x2780, v1
	v_mad_i64_i32 v[0:1], s[6:7], v0, s9, 0
	v_lshlrev_b32_e32 v2, 4, v2
	v_or_b32_e32 v0, v0, v2
	v_lshl_add_u64 v[64:65], s[54:55], 0, v[0:1]
	v_or_b32_e32 v0, s4, v70
	v_add_u32_e32 v0, v0, v6
	v_mad_i64_i32 v[0:1], s[6:7], v0, s9, 0
	s_waitcnt vmcnt(0)
	v_or_b32_e32 v0, v0, v2
	v_lshl_add_u64 v[66:67], s[38:39], 0, v[0:1]
	v_mov_b32_e32 v0, 0
	s_mov_b64 s[6:7], 0
	s_mov_b32 s9, 0
	v_mov_b32_e32 v1, v0
	v_mov_b32_e32 v2, v0
	v_mov_b32_e32 v3, v0
	v_mov_b32_e32 v4, v0
	v_mov_b32_e32 v5, v0
	v_mov_b32_e32 v6, v0
	v_mov_b32_e32 v7, v0
	v_mov_b32_e32 v8, v0
	v_mov_b32_e32 v9, v0
	v_mov_b32_e32 v10, v0
	v_mov_b32_e32 v11, v0
	s_waitcnt vmcnt(0)
	v_mov_b32_e32 v12, v0
	v_mov_b32_e32 v13, v0
	v_mov_b32_e32 v14, v0
	v_mov_b32_e32 v15, v0
	v_mov_b32_e32 v16, v0
	v_mov_b32_e32 v17, v0
	v_mov_b32_e32 v18, v0
	v_mov_b32_e32 v19, v0
	v_mov_b32_e32 v20, v0
	v_mov_b32_e32 v21, v0
	v_mov_b32_e32 v22, v0
	v_mov_b32_e32 v23, v0
	v_mov_b32_e32 v24, v0
	v_mov_b32_e32 v25, v0
	v_mov_b32_e32 v26, v0
	v_mov_b32_e32 v27, v0
	v_mov_b32_e32 v28, v0
	v_mov_b32_e32 v29, v0
	v_mov_b32_e32 v30, v0
	v_mov_b32_e32 v31, v0
	v_mov_b32_e32 v32, v0
	v_mov_b32_e32 v33, v0
	v_mov_b32_e32 v34, v0
	v_mov_b32_e32 v35, v0
	v_mov_b32_e32 v36, v0
	v_mov_b32_e32 v37, v0
	v_mov_b32_e32 v38, v0
	v_mov_b32_e32 v39, v0
	v_mov_b32_e32 v40, v0
	v_mov_b32_e32 v41, v0
	v_mov_b32_e32 v42, v0
	v_mov_b32_e32 v43, v0
	v_mov_b32_e32 v44, v0
	v_mov_b32_e32 v45, v0
	v_mov_b32_e32 v46, v0
	v_mov_b32_e32 v47, v0
	v_mov_b32_e32 v48, v0
	v_mov_b32_e32 v49, v0
	v_mov_b32_e32 v50, v0
	v_mov_b32_e32 v51, v0
	v_mov_b32_e32 v52, v0
	v_mov_b32_e32 v53, v0
	v_mov_b32_e32 v54, v0
	v_mov_b32_e32 v55, v0
	v_mov_b32_e32 v56, v0
	v_mov_b32_e32 v57, v0
	v_mov_b32_e32 v58, v0
	v_mov_b32_e32 v59, v0
	v_mov_b32_e32 v60, v0
	v_mov_b32_e32 v61, v0
	v_mov_b32_e32 v62, v0
	v_mov_b32_e32 v63, v0
	s_mov_b64 s[12:13], 0x41080
	s_mov_b64 s[14:15], 0x82080
	s_mov_b64 s[16:17], 0xc3080
	v_readlane_b32 s53, v246, 26
	v_readlane_b32 s56, v246, 29
	v_readlane_b32 s57, v246, 30
	v_readlane_b32 s58, v246, 31
	v_readlane_b32 s59, v246, 32
	v_readlane_b32 s60, v246, 33
	v_readlane_b32 s61, v246, 34
	v_readlane_b32 s62, v246, 35
	v_readlane_b32 s63, v246, 36
	v_readlane_b32 s64, v246, 37
	v_readlane_b32 s65, v246, 38
	v_readlane_b32 s66, v246, 39
	v_readlane_b32 s67, v246, 40
	v_readlane_b32 s37, v246, 10
	v_readlane_b32 s40, v246, 13
	v_readlane_b32 s41, v246, 14
	v_readlane_b32 s42, v246, 15
	v_readlane_b32 s43, v246, 16
	v_readlane_b32 s44, v246, 17
	v_readlane_b32 s45, v246, 18
	v_readlane_b32 s46, v246, 19
	v_readlane_b32 s47, v246, 20
	v_readlane_b32 s48, v246, 21
	v_readlane_b32 s49, v246, 22
	v_readlane_b32 s50, v246, 23
	v_readlane_b32 s51, v246, 24
	s_waitcnt vmcnt(0) lgkmcnt(0)
	s_barrier
	s_bitcmp1_b32 s68, 8
	s_cbranch_scc0 gp62_skip
	s_setprio 3

.LBB0_149:
	s_mov_b64 s[4:5], -1
	s_and_b64 vcc, exec, s[0:1]
	s_cbranch_vccz .LBB0_141
	v_mov_b32_e32 v69, v139
	v_readlane_b32 s36, v246, 9
	v_ashrrev_i32_e32 v72, 6, v69
	s_waitcnt vmcnt(48)
	v_lshlrev_b32_e32 v6, 3, v72
	v_bfe_u32 v68, v69, 3, 3
	v_or_b32_e32 v2, v6, v68
	v_lshrrev_b32_e32 v7, 1, v2
	s_lshl_b32 s1, s7, 7
	v_xor_b32_e32 v3, v7, v69
	v_readlane_b32 s50, v246, 23
	v_readlane_b32 s51, v246, 24
	s_lshl_b32 s0, s8, 7
	v_add_u32_e32 v4, s1, v2
	s_movk_i32 s7, 0x880
	v_readlane_b32 s37, v246, 10
	v_mov_b64_e32 v[0:1], s[50:51]
	v_lshlrev_b32_e32 v3, 4, v3
	v_mad_i64_i32 v[0:1], s[4:5], v4, s7, v[0:1]
	v_and_b32_e32 v136, 0x70, v3
	v_add_u32_e32 v4, s0, v2
	v_mov_b64_e32 v[2:3], s[36:37]
	v_mad_i64_i32 v[2:3], s[4:5], v4, s7, v[2:3]
	v_lshlrev_b32_e32 v74, 10, v72
	v_add_u32_e32 v4, 0x4000, v74
	v_readfirstlane_b32 s4, v74
	v_lshl_add_u64 v[0:1], v[0:1], 0, v[136:137]
	s_mov_b32 m0, s4
	v_readfirstlane_b32 s4, v4
	v_add_u32_e32 v9, 0x1000, v74
	v_lshl_add_u64 v[2:3], v[2:3], 0, v[136:137]
	global_load_lds_dwordx4 v[0:1], off
	s_mov_b32 m0, s4
	s_mov_b64 s[8:9], 0x11000
	v_readfirstlane_b32 s4, v9
	v_add_u32_e32 v9, 0x5000, v74
	global_load_lds_dwordx4 v[2:3], off
	v_lshl_add_u64 v[4:5], v[0:1], 0, s[8:9]
	s_mov_b32 m0, s4
	v_readfirstlane_b32 s4, v9
	v_add_u32_e32 v9, 0x2000, v74
	global_load_lds_dwordx4 v[4:5], off
	v_lshl_add_u64 v[4:5], v[2:3], 0, s[8:9]
	s_mov_b32 m0, s4
	s_mov_b64 s[8:9], 0x22000
	v_readfirstlane_b32 s4, v9
	v_add_u32_e32 v9, 0x6000, v74
	global_load_lds_dwordx4 v[4:5], off
	v_lshl_add_u64 v[4:5], v[0:1], 0, s[8:9]
	s_mov_b32 m0, s4
	v_readfirstlane_b32 s4, v9
	global_load_lds_dwordx4 v[4:5], off
	v_lshl_add_u64 v[4:5], v[2:3], 0, s[8:9]
	s_mov_b32 m0, s4
	s_mov_b64 s[8:9], 0x33000
	global_load_lds_dwordx4 v[4:5], off
	v_add_u32_e32 v4, 0x3000, v74
	v_lshl_add_u64 v[0:1], v[0:1], 0, s[8:9]
	v_readfirstlane_b32 s4, v4
	s_mov_b32 m0, s4
	v_bfe_u32 v71, v69, 4, 2
	global_load_lds_dwordx4 v[0:1], off
	v_lshl_add_u64 v[0:1], v[2:3], 0, s[8:9]
	v_add_u32_e32 v2, 0x7000, v74
	v_and_b32_e32 v73, 15, v69
	v_readfirstlane_b32 s4, v2
	s_mov_b32 m0, s4
	v_lshrrev_b32_e32 v8, 1, v69
	global_load_lds_dwordx4 v[0:1], off
	v_ashrrev_i32_e32 v1, 1, v69
	v_bfe_u32 v0, v69, 1, 3
	v_and_b32_e32 v70, 0xffffffc0, v1
	v_or_b32_e32 v1, v70, v73
	v_bitop3_b32 v0, v71, v0, 4 bitop3:0x36
	v_lshlrev_b32_e32 v75, 7, v1
	v_bitop3_b32 v1, v71, v8, 7 bitop3:0x78
	v_lshlrev_b32_e32 v78, 4, v0
	v_or_b32_e32 v0, s1, v68
	v_lshlrev_b32_e32 v76, 4, v1
	v_lshlrev_b32_e32 v1, 7, v69
	v_add_u32_e32 v0, v0, v6
	v_bitop3_b32 v2, v7, 7, v69 bitop3:0x48
	v_and_b32_e32 v77, 0x2780, v1
	v_mad_i64_i32 v[0:1], s[4:5], v0, s7, 0
	v_lshlrev_b32_e32 v2, 4, v2
	v_or_b32_e32 v0, v0, v2
	v_lshl_add_u64 v[64:65], s[50:51], 0, v[0:1]
	v_or_b32_e32 v0, s0, v68
	v_add_u32_e32 v0, v0, v6
	v_mad_i64_i32 v[0:1], s[4:5], v0, s7, 0
	s_waitcnt vmcnt(0)
	v_or_b32_e32 v0, v0, v2
	v_lshl_add_u64 v[66:67], s[36:37], 0, v[0:1]
	v_mov_b32_e32 v0, 0
	s_mov_b32 s7, 0
	s_mov_b64 s[4:5], 0
	v_mov_b32_e32 v1, v0
	v_mov_b32_e32 v2, v0
	v_mov_b32_e32 v3, v0
	v_mov_b32_e32 v4, v0
	v_mov_b32_e32 v5, v0
	v_mov_b32_e32 v6, v0
	v_mov_b32_e32 v7, v0
	v_mov_b32_e32 v8, v0
	v_mov_b32_e32 v9, v0
	v_mov_b32_e32 v10, v0
	v_mov_b32_e32 v11, v0
	s_waitcnt vmcnt(0)
	v_mov_b32_e32 v12, v0
	v_mov_b32_e32 v13, v0
	v_mov_b32_e32 v14, v0
	v_mov_b32_e32 v15, v0
	v_mov_b32_e32 v16, v0
	v_mov_b32_e32 v17, v0
	v_mov_b32_e32 v18, v0
	v_mov_b32_e32 v19, v0
	v_mov_b32_e32 v20, v0
	v_mov_b32_e32 v21, v0
	v_mov_b32_e32 v22, v0
	v_mov_b32_e32 v23, v0
	v_mov_b32_e32 v24, v0
	v_mov_b32_e32 v25, v0
	v_mov_b32_e32 v26, v0
	v_mov_b32_e32 v27, v0
	v_mov_b32_e32 v28, v0
	v_mov_b32_e32 v29, v0
	v_mov_b32_e32 v30, v0
	v_mov_b32_e32 v31, v0
	v_mov_b32_e32 v32, v0
	v_mov_b32_e32 v33, v0
	v_mov_b32_e32 v34, v0
	v_mov_b32_e32 v35, v0
	v_mov_b32_e32 v36, v0
	v_mov_b32_e32 v37, v0
	v_mov_b32_e32 v38, v0
	v_mov_b32_e32 v39, v0
	v_mov_b32_e32 v40, v0
	v_mov_b32_e32 v41, v0
	v_mov_b32_e32 v42, v0
	v_mov_b32_e32 v43, v0
	v_mov_b32_e32 v44, v0
	v_mov_b32_e32 v45, v0
	v_mov_b32_e32 v46, v0
	v_mov_b32_e32 v47, v0
	v_mov_b32_e32 v48, v0
	v_mov_b32_e32 v49, v0
	v_mov_b32_e32 v50, v0
	v_mov_b32_e32 v51, v0
	v_mov_b32_e32 v52, v0
	v_mov_b32_e32 v53, v0
	v_mov_b32_e32 v54, v0
	v_mov_b32_e32 v55, v0
	v_mov_b32_e32 v56, v0
	v_mov_b32_e32 v57, v0
	v_mov_b32_e32 v58, v0
	v_mov_b32_e32 v59, v0
	v_mov_b32_e32 v60, v0
	v_mov_b32_e32 v61, v0
	v_mov_b32_e32 v62, v0
	v_mov_b32_e32 v63, v0
	s_mov_b64 s[10:11], 0x11080
	s_mov_b64 s[12:13], 0x33080
	s_mov_b64 s[14:15], 0x22080
	v_readlane_b32 s38, v246, 11
	v_readlane_b32 s39, v246, 12
	v_readlane_b32 s40, v246, 13
	v_readlane_b32 s41, v246, 14
	v_readlane_b32 s42, v246, 15
	v_readlane_b32 s43, v246, 16
	v_readlane_b32 s44, v246, 17
	v_readlane_b32 s45, v246, 18
	v_readlane_b32 s46, v246, 19
	v_readlane_b32 s47, v246, 20
	v_readlane_b32 s48, v246, 21
	v_readlane_b32 s49, v246, 22
	s_waitcnt vmcnt(0) lgkmcnt(0)
	s_barrier
	s_bitcmp1_b32 s68, 8
	s_cbranch_scc0 gp151_skip
	s_setprio 3

.LBB0_170:
	s_mov_b64 s[6:7], -1
	s_and_b64 vcc, exec, s[4:5]
	s_cbranch_vccz .LBB0_162
	v_mov_b32_e32 v71, v139
	v_readlane_b32 s40, v246, 9
	v_ashrrev_i32_e32 v68, 6, v71
	s_waitcnt vmcnt(48)
	v_lshlrev_b32_e32 v6, 3, v68
	v_bfe_u32 v70, v71, 3, 3
	s_lshl_b32 s5, s9, 7
	v_or_b32_e32 v2, v6, v70
	v_readlane_b32 s54, v246, 23
	v_readlane_b32 s55, v246, 24
	v_lshrrev_b32_e32 v7, 1, v2
	v_add_u32_e32 v4, s5, v2
	v_readlane_b32 s41, v246, 10
	v_readlane_b32 s42, v246, 11
	v_readlane_b32 s43, v246, 12
	v_readlane_b32 s44, v246, 13
	v_readlane_b32 s45, v246, 14
	v_readlane_b32 s46, v246, 15
	v_readlane_b32 s47, v246, 16
	v_readlane_b32 s48, v246, 17
	v_readlane_b32 s49, v246, 18
	v_readlane_b32 s50, v246, 19
	v_readlane_b32 s51, v246, 20
	v_mov_b64_e32 v[0:1], s[54:55]
	v_xor_b32_e32 v3, v7, v71
	v_mad_i64_i32 v[0:1], s[6:7], v4, s36, v[0:1]
	v_readlane_b32 s36, v247, 57
	s_lshl_b32 s4, s10, 7
	v_lshlrev_b32_e32 v3, 4, v3
	v_readlane_b32 s50, v246, 7
	v_readlane_b32 s51, v246, 8
	v_and_b32_e32 v136, 0x70, v3
	v_add_u32_e32 v4, s4, v2
	s_movk_i32 s9, 0x880
	v_mov_b64_e32 v[2:3], s[50:51]
	v_mad_i64_i32 v[2:3], s[6:7], v4, s9, v[2:3]
	v_lshlrev_b32_e32 v72, 10, v68
	v_add_u32_e32 v4, 0x4000, v72
	v_readfirstlane_b32 s6, v72
	v_lshl_add_u64 v[0:1], v[0:1], 0, v[136:137]
	s_mov_b32 m0, s6
	v_readfirstlane_b32 s6, v4
	v_add_u32_e32 v9, 0x1000, v72
	v_lshl_add_u64 v[2:3], v[2:3], 0, v[136:137]
	global_load_lds_dwordx4 v[0:1], off
	s_mov_b32 m0, s6
	s_mov_b64 s[10:11], 0x11000
	v_readfirstlane_b32 s6, v9
	v_add_u32_e32 v9, 0x5000, v72
	global_load_lds_dwordx4 v[2:3], off
	v_lshl_add_u64 v[4:5], v[0:1], 0, s[10:11]
	s_mov_b32 m0, s6
	v_readfirstlane_b32 s6, v9
	v_add_u32_e32 v9, 0x2000, v72
	global_load_lds_dwordx4 v[4:5], off
	v_lshl_add_u64 v[4:5], v[2:3], 0, s[10:11]
	s_mov_b32 m0, s6
	s_mov_b64 s[10:11], 0x22000
	v_readfirstlane_b32 s6, v9
	v_add_u32_e32 v9, 0x6000, v72
	global_load_lds_dwordx4 v[4:5], off
	v_lshl_add_u64 v[4:5], v[0:1], 0, s[10:11]
	s_mov_b32 m0, s6
	v_readfirstlane_b32 s6, v9
	global_load_lds_dwordx4 v[4:5], off
	v_lshl_add_u64 v[4:5], v[2:3], 0, s[10:11]
	s_mov_b32 m0, s6
	s_mov_b64 s[10:11], 0x33000
	global_load_lds_dwordx4 v[4:5], off
	v_add_u32_e32 v4, 0x3000, v72
	v_lshl_add_u64 v[0:1], v[0:1], 0, s[10:11]
	v_readfirstlane_b32 s6, v4
	s_mov_b32 m0, s6
	v_bfe_u32 v75, v71, 4, 2
	global_load_lds_dwordx4 v[0:1], off
	v_lshl_add_u64 v[0:1], v[2:3], 0, s[10:11]
	v_add_u32_e32 v2, 0x7000, v72
	v_and_b32_e32 v76, 15, v71
	v_readfirstlane_b32 s6, v2
	s_mov_b32 m0, s6
	v_lshrrev_b32_e32 v8, 1, v71
	global_load_lds_dwordx4 v[0:1], off
	v_ashrrev_i32_e32 v1, 1, v71
	v_bfe_u32 v0, v71, 1, 3
	v_and_b32_e32 v69, 0xffffffc0, v1
	v_or_b32_e32 v1, v69, v76
	v_bitop3_b32 v0, v75, v0, 4 bitop3:0x36
	v_lshlrev_b32_e32 v73, 7, v1
	v_bitop3_b32 v1, v75, v8, 7 bitop3:0x78
	v_lshlrev_b32_e32 v77, 4, v0
	v_or_b32_e32 v0, s5, v70
	v_lshlrev_b32_e32 v78, 4, v1
	v_lshlrev_b32_e32 v1, 7, v71
	v_add_u32_e32 v0, v0, v6
	v_bitop3_b32 v2, v7, 7, v71 bitop3:0x48
	v_and_b32_e32 v74, 0x2780, v1
	v_mad_i64_i32 v[0:1], s[6:7], v0, s9, 0
	v_lshlrev_b32_e32 v2, 4, v2
	v_or_b32_e32 v0, v0, v2
	v_lshl_add_u64 v[64:65], s[54:55], 0, v[0:1]
	v_or_b32_e32 v0, s4, v70
	v_add_u32_e32 v0, v0, v6
	v_mad_i64_i32 v[0:1], s[6:7], v0, s9, 0
	s_waitcnt vmcnt(0)
	v_or_b32_e32 v0, v0, v2
	v_lshl_add_u64 v[66:67], s[50:51], 0, v[0:1]
	v_mov_b32_e32 v0, 0
	s_mov_b64 s[6:7], 0
	s_mov_b32 s9, 0
	v_mov_b32_e32 v1, v0
	v_mov_b32_e32 v2, v0
	v_mov_b32_e32 v3, v0
	v_mov_b32_e32 v4, v0
	v_mov_b32_e32 v5, v0
	v_mov_b32_e32 v6, v0
	v_mov_b32_e32 v7, v0
	v_mov_b32_e32 v8, v0
	v_mov_b32_e32 v9, v0
	v_mov_b32_e32 v10, v0
	v_mov_b32_e32 v11, v0
	s_waitcnt vmcnt(0)
	v_mov_b32_e32 v12, v0
	v_mov_b32_e32 v13, v0
	v_mov_b32_e32 v14, v0
	v_mov_b32_e32 v15, v0
	v_mov_b32_e32 v16, v0
	v_mov_b32_e32 v17, v0
	v_mov_b32_e32 v18, v0
	v_mov_b32_e32 v19, v0
	v_mov_b32_e32 v20, v0
	v_mov_b32_e32 v21, v0
	v_mov_b32_e32 v22, v0
	v_mov_b32_e32 v23, v0
	v_mov_b32_e32 v24, v0
	v_mov_b32_e32 v25, v0
	v_mov_b32_e32 v26, v0
	v_mov_b32_e32 v27, v0
	v_mov_b32_e32 v28, v0
	v_mov_b32_e32 v29, v0
	v_mov_b32_e32 v30, v0
	v_mov_b32_e32 v31, v0
	v_mov_b32_e32 v32, v0
	v_mov_b32_e32 v33, v0
	v_mov_b32_e32 v34, v0
	v_mov_b32_e32 v35, v0
	v_mov_b32_e32 v36, v0
	v_mov_b32_e32 v37, v0
	v_mov_b32_e32 v38, v0
	v_mov_b32_e32 v39, v0
	v_mov_b32_e32 v40, v0
	v_mov_b32_e32 v41, v0
	v_mov_b32_e32 v42, v0
	v_mov_b32_e32 v43, v0
	v_mov_b32_e32 v44, v0
	v_mov_b32_e32 v45, v0
	v_mov_b32_e32 v46, v0
	v_mov_b32_e32 v47, v0
	v_mov_b32_e32 v48, v0
	v_mov_b32_e32 v49, v0
	v_mov_b32_e32 v50, v0
	v_mov_b32_e32 v51, v0
	v_mov_b32_e32 v52, v0
	v_mov_b32_e32 v53, v0
	v_mov_b32_e32 v54, v0
	v_mov_b32_e32 v55, v0
	v_mov_b32_e32 v56, v0
	v_mov_b32_e32 v57, v0
	v_mov_b32_e32 v58, v0
	v_mov_b32_e32 v59, v0
	v_mov_b32_e32 v60, v0
	v_mov_b32_e32 v61, v0
	v_mov_b32_e32 v62, v0
	v_mov_b32_e32 v63, v0
	s_mov_b64 s[12:13], 0x11080
	s_mov_b64 s[14:15], 0x33080
	s_mov_b64 s[16:17], 0x22080
	v_readlane_b32 s52, v246, 21
	v_readlane_b32 s53, v246, 22
	v_readlane_b32 s37, v247, 58
	v_readlane_b32 s38, v247, 59
	v_readlane_b32 s39, v247, 60
	v_readlane_b32 s40, v247, 61
	v_readlane_b32 s41, v247, 62
	v_readlane_b32 s42, v247, 63
	v_readlane_b32 s43, v246, 0
	v_readlane_b32 s44, v246, 1
	v_readlane_b32 s45, v246, 2
	v_readlane_b32 s46, v246, 3
	v_readlane_b32 s47, v246, 4
	v_readlane_b32 s48, v246, 5
	v_readlane_b32 s49, v246, 6
	s_waitcnt vmcnt(0) lgkmcnt(0)
	s_barrier
	s_bitcmp1_b32 s68, 8
	s_cbranch_scc0 gp172_skip
	s_setprio 3

.LBB0_1105:
	v_mov_b32_e32 v69, v139
	v_readlane_b32 s40, v246, 9
	v_ashrrev_i32_e32 v72, 6, v69
	v_lshlrev_b32_e32 v6, 3, v72
	v_bfe_u32 v68, v69, 3, 3
	s_lshl_b32 s1, s7, 7
	s_waitcnt lgkmcnt(0)
	v_or_b32_e32 v2, v6, v68
	v_readlane_b32 s54, v246, 23
	v_readlane_b32 s55, v246, 24
	v_lshrrev_b32_e32 v7, 1, v2
	v_add_u32_e32 v4, s1, v2
	v_readlane_b32 s41, v246, 10
	v_readlane_b32 s42, v246, 11
	v_readlane_b32 s43, v246, 12
	v_readlane_b32 s44, v246, 13
	v_readlane_b32 s45, v246, 14
	v_readlane_b32 s46, v246, 15
	v_readlane_b32 s47, v246, 16
	v_readlane_b32 s48, v246, 17
	v_readlane_b32 s49, v246, 18
	v_readlane_b32 s50, v246, 19
	v_readlane_b32 s51, v246, 20
	v_mov_b64_e32 v[0:1], s[54:55]
	v_xor_b32_e32 v3, v7, v69
	v_mad_i64_i32 v[0:1], s[4:5], v4, s36, v[0:1]
	v_readlane_b32 s36, v247, 57
	s_lshl_b32 s0, s8, 7
	v_lshlrev_b32_e32 v3, 4, v3
	v_readlane_b32 s48, v246, 5
	v_readlane_b32 s49, v246, 6
	v_and_b32_e32 v136, 0x70, v3
	v_add_u32_e32 v4, s0, v2
	s_movk_i32 s9, 0x880
	v_mov_b64_e32 v[2:3], s[48:49]
	v_mad_i64_i32 v[2:3], s[4:5], v4, s9, v[2:3]
	v_lshlrev_b32_e32 v74, 10, v72
	v_add_u32_e32 v4, 0x4000, v74
	v_readfirstlane_b32 s4, v74
	v_lshl_add_u64 v[0:1], v[0:1], 0, v[136:137]
	s_mov_b32 m0, s4
	v_readfirstlane_b32 s4, v4
	v_add_u32_e32 v9, 0x1000, v74
	v_lshl_add_u64 v[2:3], v[2:3], 0, v[136:137]
	global_load_lds_dwordx4 v[0:1], off
	s_mov_b32 m0, s4
	s_mov_b64 s[10:11], 0x11000
	v_readfirstlane_b32 s4, v9
	v_add_u32_e32 v9, 0x5000, v74
	global_load_lds_dwordx4 v[2:3], off
	v_lshl_add_u64 v[4:5], v[0:1], 0, s[10:11]
	s_mov_b32 m0, s4
	v_readfirstlane_b32 s4, v9
	v_add_u32_e32 v9, 0x2000, v74
	global_load_lds_dwordx4 v[4:5], off
	v_lshl_add_u64 v[4:5], v[2:3], 0, s[10:11]
	s_mov_b32 m0, s4
	s_mov_b64 s[10:11], 0x22000
	v_readfirstlane_b32 s4, v9
	v_add_u32_e32 v9, 0x6000, v74
	global_load_lds_dwordx4 v[4:5], off
	v_lshl_add_u64 v[4:5], v[0:1], 0, s[10:11]
	s_mov_b32 m0, s4
	v_readfirstlane_b32 s4, v9
	global_load_lds_dwordx4 v[4:5], off
	v_lshl_add_u64 v[4:5], v[2:3], 0, s[10:11]
	s_mov_b32 m0, s4
	s_mov_b64 s[10:11], 0x33000
	global_load_lds_dwordx4 v[4:5], off
	v_add_u32_e32 v4, 0x3000, v74
	v_lshl_add_u64 v[0:1], v[0:1], 0, s[10:11]
	v_readfirstlane_b32 s4, v4
	s_mov_b32 m0, s4
	v_bfe_u32 v71, v69, 4, 2
	global_load_lds_dwordx4 v[0:1], off
	v_lshl_add_u64 v[0:1], v[2:3], 0, s[10:11]
	v_add_u32_e32 v2, 0x7000, v74
	v_and_b32_e32 v73, 15, v69
	v_readfirstlane_b32 s4, v2
	s_mov_b32 m0, s4
	v_lshrrev_b32_e32 v8, 1, v69
	global_load_lds_dwordx4 v[0:1], off
	v_ashrrev_i32_e32 v1, 1, v69
	v_bfe_u32 v0, v69, 1, 3
	v_and_b32_e32 v70, 0xffffffc0, v1
	v_or_b32_e32 v1, v70, v73
	v_bitop3_b32 v0, v71, v0, 4 bitop3:0x36
	v_lshlrev_b32_e32 v75, 7, v1
	v_bitop3_b32 v1, v71, v8, 7 bitop3:0x78
	v_lshlrev_b32_e32 v78, 4, v0
	v_or_b32_e32 v0, s1, v68
	v_lshlrev_b32_e32 v76, 4, v1
	v_lshlrev_b32_e32 v1, 7, v69
	v_add_u32_e32 v0, v0, v6
	v_bitop3_b32 v2, v7, 7, v69 bitop3:0x48
	v_and_b32_e32 v77, 0x2780, v1
	v_mad_i64_i32 v[0:1], s[4:5], v0, s9, 0
	v_lshlrev_b32_e32 v2, 4, v2
	v_or_b32_e32 v0, v0, v2
	v_lshl_add_u64 v[64:65], s[54:55], 0, v[0:1]
	v_or_b32_e32 v0, s0, v68
	v_add_u32_e32 v0, v0, v6
	v_mad_i64_i32 v[0:1], s[4:5], v0, s9, 0
	s_waitcnt vmcnt(0)
	v_or_b32_e32 v0, v0, v2
	v_lshl_add_u64 v[66:67], s[48:49], 0, v[0:1]
	v_mov_b32_e32 v0, 0
	s_mov_b32 s9, 0
	s_mov_b64 s[4:5], 0
	v_mov_b32_e32 v1, v0
	v_mov_b32_e32 v2, v0
	v_mov_b32_e32 v3, v0
	v_mov_b32_e32 v4, v0
	v_mov_b32_e32 v5, v0
	v_mov_b32_e32 v6, v0
	v_mov_b32_e32 v7, v0
	v_mov_b32_e32 v8, v0
	v_mov_b32_e32 v9, v0
	v_mov_b32_e32 v10, v0
	v_mov_b32_e32 v11, v0
	v_mov_b32_e32 v12, v0
	v_mov_b32_e32 v13, v0
	v_mov_b32_e32 v14, v0
	v_mov_b32_e32 v15, v0
	v_mov_b32_e32 v16, v0
	v_mov_b32_e32 v17, v0
	v_mov_b32_e32 v18, v0
	v_mov_b32_e32 v19, v0
	v_mov_b32_e32 v20, v0
	v_mov_b32_e32 v21, v0
	v_mov_b32_e32 v22, v0
	v_mov_b32_e32 v23, v0
	v_mov_b32_e32 v24, v0
	v_mov_b32_e32 v25, v0
	v_mov_b32_e32 v26, v0
	v_mov_b32_e32 v27, v0
	v_mov_b32_e32 v28, v0
	v_mov_b32_e32 v29, v0
	v_mov_b32_e32 v30, v0
	v_mov_b32_e32 v31, v0
	v_mov_b32_e32 v32, v0
	v_mov_b32_e32 v33, v0
	v_mov_b32_e32 v34, v0
	v_mov_b32_e32 v35, v0
	v_mov_b32_e32 v36, v0
	v_mov_b32_e32 v37, v0
	v_mov_b32_e32 v38, v0
	v_mov_b32_e32 v39, v0
	v_mov_b32_e32 v40, v0
	v_mov_b32_e32 v41, v0
	v_mov_b32_e32 v42, v0
	v_mov_b32_e32 v43, v0
	v_mov_b32_e32 v44, v0
	v_mov_b32_e32 v45, v0
	v_mov_b32_e32 v46, v0
	v_mov_b32_e32 v47, v0
	v_mov_b32_e32 v48, v0
	v_mov_b32_e32 v49, v0
	v_mov_b32_e32 v50, v0
	v_mov_b32_e32 v51, v0
	v_mov_b32_e32 v52, v0
	v_mov_b32_e32 v53, v0
	v_mov_b32_e32 v54, v0
	v_mov_b32_e32 v55, v0
	v_mov_b32_e32 v56, v0
	v_mov_b32_e32 v57, v0
	v_mov_b32_e32 v58, v0
	v_mov_b32_e32 v59, v0
	v_mov_b32_e32 v60, v0
	v_mov_b32_e32 v61, v0
	v_mov_b32_e32 v62, v0
	v_mov_b32_e32 v63, v0
	s_mov_b64 s[12:13], 0x11080
	s_mov_b64 s[14:15], 0x33080
	s_mov_b64 s[16:17], 0x22080
	v_readlane_b32 s52, v246, 21
	v_readlane_b32 s53, v246, 22
	v_readlane_b32 s37, v247, 58
	v_readlane_b32 s38, v247, 59
	v_readlane_b32 s39, v247, 60
	v_readlane_b32 s40, v247, 61
	v_readlane_b32 s41, v247, 62
	v_readlane_b32 s42, v247, 63
	v_readlane_b32 s43, v246, 0
	v_readlane_b32 s44, v246, 1
	v_readlane_b32 s45, v246, 2
	v_readlane_b32 s46, v246, 3
	v_readlane_b32 s47, v246, 4
	v_readlane_b32 s50, v246, 7
	v_readlane_b32 s51, v246, 8
	s_waitcnt vmcnt(0) lgkmcnt(0)
	s_barrier
	s_bitcmp1_b32 s68, 8
	s_cbranch_scc0 gp1106_skip
	s_setprio 3
